# hyena epilogue 0: parameter and first row-batch loads requested right after conv 0, before the K-split reduction barriers
# baseline (speedup 1.0000x reference)
; DI void hyena_item(const P& p, int l, int c, char* smem) {
;     ...
;   if (cwv) {
;     const float d0 = p.fbias[(size_t)(l * 2 + 0) * 512 + c];
;     const float v0 = cw[c], v1 = cw[1536 + c], v2 = cw[3072 + c], vb = cbias[c];
;     const float x0 = cw[512 + c], x1 = cw[1536 + 512 + c], x2 = cw[3072 + 512 + c], xb = cbias[512 + c];
;     const u16* rowv = p.hyT + (size_t)c * HYP + bt * SEQ;
;     const u16* rowx = p.hyT + (size_t)(512 + c) * HYP + bt * SEQ;
; #pragma unroll
;     for (int I = 0; I < 4; ++I)
; #pragma unroll
;       for (int rq = 0; rq < 4; ++rq) {
;         const int bq = 32 * I + 8 * rq + 4 * g;
;         const int t4 = 128 * a + bq;
;         float pv[4], px[4];
;         sconv4(rowv, t4, v0, v1, v2, vb, pv);
;         sconv4(rowx, t4, x0, x1, x2, xb, px);
.Lhc0_done:
.LBB0_437:
	s_or_b64 exec, exec, s[78:79]
	v_or_b32_e32 v231, v231, v223
	v_lshrrev_b32_e32 v230, 4, v230
	v_lshlrev_b32_e32 v186, 2, v188
	v_lshlrev_b32_e32 v187, 7, v231
	v_lshlrev_b32_e32 v232, 13, v230
	v_lshlrev_b32_e32 v184, 14, v230
	v_or_b32_e32 v233, v187, v186
	v_cmp_lt_i32_e32 vcc, 0, v250
	s_cbranch_vccz .Lhy0_noissue
	v_readlane_b32 s88, v248, 24
	s_nop 1
	s_add_i32 s88, s72, s88
	s_mov_b32 s89, s57
	s_lshl_b64 s[88:89], s[88:89], 2
	s_add_u32 s88, s20, s88
	s_addc_u32 s89, s21, s89
	global_load_dword v239, v189, s[88:89]
	global_load_dword v240, v189, s[74:75]
	global_load_dword v241, v189, s[80:81]
	global_load_dword v242, v189, s[82:83]
	global_load_dword v243, v189, s[84:85]
	global_load_dword v247, v189, s[84:85] offset:2048
	global_load_dword v244, v189, s[74:75] offset:2048
	global_load_dword v245, v204, s[74:75]
	global_load_dword v246, v205, s[74:75] offset:2048
	s_add_u32 s100, s86, -4
	s_addc_u32 s101, s87, -1
	s_or_b32 s98, s72, 0x200
	s_mul_hi_u32 s99, s98, 0x8080
	s_mul_i32 s98, s98, 0x8080
	s_add_u32 s98, s36, s98
	s_addc_u32 s99, s37, s99
	s_add_u32 s98, s98, -4
	s_addc_u32 s99, s99, -1
	v_lshl_add_u32 v234, v233, 1, v184
	global_load_dwordx4 v[72:75], v234, s[100:101] offset:0
	global_load_dwordx4 v[76:79], v234, s[98:99] offset:0
	global_load_dwordx4 v[80:83], v234, s[100:101] offset:16
	global_load_dwordx4 v[84:87], v234, s[98:99] offset:16
	global_load_dwordx4 v[88:91], v234, s[100:101] offset:32
	global_load_dwordx4 v[92:95], v234, s[98:99] offset:32
	global_load_dwordx4 v[96:99], v234, s[100:101] offset:48
	global_load_dwordx4 v[100:103], v234, s[98:99] offset:48
	global_load_dwordx4 v[104:107], v234, s[100:101] offset:64
	global_load_dwordx4 v[108:111], v234, s[98:99] offset:64
	global_load_dwordx4 v[112:115], v234, s[100:101] offset:80
	global_load_dwordx4 v[116:119], v234, s[98:99] offset:80
	global_load_dwordx4 v[120:123], v234, s[100:101] offset:96
	global_load_dwordx4 v[124:127], v234, s[98:99] offset:96
	global_load_dwordx4 v[128:131], v234, s[100:101] offset:112
	global_load_dwordx4 v[132:135], v234, s[98:99] offset:112
.Lhy0_noissue:
	s_waitcnt lgkmcnt(0)
	s_barrier
	v_and_b32_e32 v249, 0xff, v198
	v_lshlrev_b32_e32 v249, 4, v249
	v_cmp_lt_i32_e32 vcc, 0, v250
	s_cbranch_vccnz .Lhy0_rd_main
	s_nop 15
	ds_write_b128 v249, v[0:3] offset:0
	ds_write_b128 v249, v[4:7] offset:4096
	ds_write_b128 v249, v[8:11] offset:8192
	ds_write_b128 v249, v[12:15] offset:12288
	ds_write_b128 v249, v[16:19] offset:16384
	ds_write_b128 v249, v[20:23] offset:20480
	ds_write_b128 v249, v[24:27] offset:24576
	ds_write_b128 v249, v[28:31] offset:28672
	ds_write_b128 v249, v[32:35] offset:32768
	ds_write_b128 v249, v[36:39] offset:36864
	ds_write_b128 v249, v[40:43] offset:40960
	ds_write_b128 v249, v[44:47] offset:45056
	ds_write_b128 v249, v[48:51] offset:49152
	ds_write_b128 v249, v[52:55] offset:53248
	ds_write_b128 v249, v[56:59] offset:57344
	ds_write_b128 v249, v[60:63] offset:61440
	s_waitcnt lgkmcnt(0)
.Lhy0_rd_main:
	s_barrier
	v_cmp_lt_i32_e32 vcc, 0, v250
	s_cbranch_vccz .Lhy0_rd_done
	ds_read_b128 v[136:139], v249 offset:0
	ds_read_b128 v[140:143], v249 offset:4096
	ds_read_b128 v[144:147], v249 offset:8192
	ds_read_b128 v[148:151], v249 offset:12288
	ds_read_b128 v[152:155], v249 offset:16384
	ds_read_b128 v[156:159], v249 offset:20480
	ds_read_b128 v[160:163], v249 offset:24576
	ds_read_b128 v[164:167], v249 offset:28672
	s_waitcnt lgkmcnt(7)
	v_add_f32_e32 v0, v0, v136
	v_add_f32_e32 v1, v1, v137
	v_add_f32_e32 v2, v2, v138
	v_add_f32_e32 v3, v3, v139
	s_waitcnt lgkmcnt(6)
	v_add_f32_e32 v4, v4, v140
	v_add_f32_e32 v5, v5, v141
	v_add_f32_e32 v6, v6, v142
	v_add_f32_e32 v7, v7, v143
	s_waitcnt lgkmcnt(5)
	v_add_f32_e32 v8, v8, v144
	v_add_f32_e32 v9, v9, v145
	v_add_f32_e32 v10, v10, v146
	v_add_f32_e32 v11, v11, v147
	s_waitcnt lgkmcnt(4)
	v_add_f32_e32 v12, v12, v148
	v_add_f32_e32 v13, v13, v149
	v_add_f32_e32 v14, v14, v150
	v_add_f32_e32 v15, v15, v151
	s_waitcnt lgkmcnt(3)
	v_add_f32_e32 v16, v16, v152
	v_add_f32_e32 v17, v17, v153
	v_add_f32_e32 v18, v18, v154
	v_add_f32_e32 v19, v19, v155
	s_waitcnt lgkmcnt(2)
	v_add_f32_e32 v20, v20, v156
	v_add_f32_e32 v21, v21, v157
	v_add_f32_e32 v22, v22, v158
	v_add_f32_e32 v23, v23, v159
	s_waitcnt lgkmcnt(1)
	v_add_f32_e32 v24, v24, v160
	v_add_f32_e32 v25, v25, v161
	v_add_f32_e32 v26, v26, v162
	v_add_f32_e32 v27, v27, v163
	s_waitcnt lgkmcnt(0)
	v_add_f32_e32 v28, v28, v164
	v_add_f32_e32 v29, v29, v165
	v_add_f32_e32 v30, v30, v166
	v_add_f32_e32 v31, v31, v167
	ds_read_b128 v[136:139], v249 offset:32768
	ds_read_b128 v[140:143], v249 offset:36864
	ds_read_b128 v[144:147], v249 offset:40960
	ds_read_b128 v[148:151], v249 offset:45056
	ds_read_b128 v[152:155], v249 offset:49152
	ds_read_b128 v[156:159], v249 offset:53248
	ds_read_b128 v[160:163], v249 offset:57344
	ds_read_b128 v[164:167], v249 offset:61440
	s_waitcnt lgkmcnt(7)
	v_add_f32_e32 v32, v32, v136
	v_add_f32_e32 v33, v33, v137
	v_add_f32_e32 v34, v34, v138
	v_add_f32_e32 v35, v35, v139
	s_waitcnt lgkmcnt(6)
	v_add_f32_e32 v36, v36, v140
	v_add_f32_e32 v37, v37, v141
	v_add_f32_e32 v38, v38, v142
	v_add_f32_e32 v39, v39, v143
	s_waitcnt lgkmcnt(5)
	v_add_f32_e32 v40, v40, v144
	v_add_f32_e32 v41, v41, v145
	v_add_f32_e32 v42, v42, v146
	v_add_f32_e32 v43, v43, v147
	s_waitcnt lgkmcnt(4)
	v_add_f32_e32 v44, v44, v148
	v_add_f32_e32 v45, v45, v149
	v_add_f32_e32 v46, v46, v150
	v_add_f32_e32 v47, v47, v151
	s_waitcnt lgkmcnt(3)
	v_add_f32_e32 v48, v48, v152
	v_add_f32_e32 v49, v49, v153
	v_add_f32_e32 v50, v50, v154
	v_add_f32_e32 v51, v51, v155
	s_waitcnt lgkmcnt(2)
	v_add_f32_e32 v52, v52, v156
	v_add_f32_e32 v53, v53, v157
	v_add_f32_e32 v54, v54, v158
	v_add_f32_e32 v55, v55, v159
	s_waitcnt lgkmcnt(1)
	v_add_f32_e32 v56, v56, v160
	v_add_f32_e32 v57, v57, v161
	v_add_f32_e32 v58, v58, v162
	v_add_f32_e32 v59, v59, v163
	s_waitcnt lgkmcnt(0)
	v_add_f32_e32 v60, v60, v164
	v_add_f32_e32 v61, v61, v165
	v_add_f32_e32 v62, v62, v166
	v_add_f32_e32 v63, v63, v167
; DI void hyena_item(const P& p, int l, int c, char* smem) {
;     ...
;   const float invn0 = 1.0f / (misc[4] + misc[5] + misc[6] + misc[7]);
;     ...
; #pragma unroll
;     for (int I = 0; I < 4; ++I)
; #pragma unroll
;       for (int rq = 0; rq < 4; ++rq) {
;         const int bq = 32 * I + 8 * rq + 4 * g;
;         const int t4 = 128 * a + bq;
;         float pv[4], px[4];
;         sconv4(rowv, t4, v0, v1, v2, vb, pv);
;         sconv4(rowx, t4, x0, x1, x2, xb, px);
;         float zz[4];
; #pragma unroll
;         for (int j = 0; j < 4; ++j) zz[j] = px[j] * (acc[I][4 * rq + j] * invn0 + pv[j] * d0);
;         uint2 ov; ov.x = pack2(zz[0], zz[1]); ov.y = pack2(zz[2], zz[3]);
;         *(uint2*)(U + (bt * 64 + a) * 136 + bq) = ov;
;       }
.Lhy0_rd_done:
	s_barrier
	s_and_saveexec_b64 s[78:79], s[6:7]
	s_cbranch_execz .LBB0_447
	v_add_f32_e32 v238, v68, v69
	v_add_f32_e32 v238, v238, v70
	v_add_f32_e32 v238, v238, v71
	v_div_scale_f32 v169, s[88:89], v238, v238, 1.0
	v_rcp_f32_e32 v170, v169
	s_nop 0
	v_fma_f32 v171, -v169, v170, 1.0
	v_fmac_f32_e32 v170, v171, v170
	v_div_scale_f32 v171, vcc, 1.0, v238, 1.0
	v_mul_f32_e32 v236, v171, v170
	v_fma_f32 v237, -v169, v236, v171
	v_fmac_f32_e32 v236, v237, v170
	v_fma_f32 v169, -v169, v236, v171
	v_div_fmas_f32 v169, v169, v170, v236
	v_div_fixup_f32 v238, v169, v238, 1.0
	v_lshl_or_b32 v235, v230, 6, v231
	v_mul_u32_u24_e32 v235, 0x110, v235
	v_lshlrev_b32_e32 v236, 1, v186
	v_add3_u32 v235, s69, v235, v236
	s_waitcnt vmcnt(8)
	v_cmp_ne_u32_e32 vcc, 0, v233
	s_nop 1
	v_and_b32_e32 v168, 0xffff0000, v72
	v_cndmask_b32_e32 v168, 0, v168, vcc
	v_lshlrev_b32_e32 v169, 16, v73
	v_and_b32_e32 v170, 0xffff0000, v73
	v_lshlrev_b32_e32 v171, 16, v74
	v_and_b32_e32 v172, 0xffff0000, v74
	v_lshlrev_b32_e32 v173, 16, v75
	v_mul_f32_e32 v174, v240, v168
	v_fmac_f32_e32 v174, v241, v169
	v_fmac_f32_e32 v174, v242, v170
	v_add_f32_e32 v174, v243, v174
	v_mul_f32_e32 v175, v240, v169
	v_fmac_f32_e32 v175, v241, v170
	v_fmac_f32_e32 v175, v242, v171
	v_add_f32_e32 v175, v243, v175
	v_mul_f32_e32 v176, v240, v170
	v_fmac_f32_e32 v176, v241, v171
	v_fmac_f32_e32 v176, v242, v172
	v_add_f32_e32 v176, v243, v176
	v_mul_f32_e32 v177, v240, v171
	v_fmac_f32_e32 v177, v241, v172
	v_fmac_f32_e32 v177, v242, v173
	v_add_f32_e32 v177, v243, v177
	v_mul_f32_e32 v174, v239, v174
	v_mul_f32_e32 v175, v239, v175
	v_mul_f32_e32 v176, v239, v176
	v_mul_f32_e32 v177, v239, v177
	v_fmac_f32_e32 v174, v238, v48
	v_fmac_f32_e32 v175, v238, v49
	v_fmac_f32_e32 v176, v238, v50
	v_fmac_f32_e32 v177, v238, v51
	v_and_b32_e32 v168, 0xffff0000, v76
	v_cndmask_b32_e32 v168, 0, v168, vcc
	v_lshlrev_b32_e32 v169, 16, v77
	v_and_b32_e32 v170, 0xffff0000, v77
	v_lshlrev_b32_e32 v171, 16, v78
	v_and_b32_e32 v172, 0xffff0000, v78
	v_lshlrev_b32_e32 v173, 16, v79
	v_mul_f32_e32 v178, v244, v168
	v_fmac_f32_e32 v178, v245, v169
	v_fmac_f32_e32 v178, v246, v170
	v_add_f32_e32 v178, v247, v178
	v_mul_f32_e32 v179, v244, v169
	v_fmac_f32_e32 v179, v245, v170
	v_fmac_f32_e32 v179, v246, v171
	v_add_f32_e32 v179, v247, v179
	v_mul_f32_e32 v180, v244, v170
	v_fmac_f32_e32 v180, v245, v171
	v_fmac_f32_e32 v180, v246, v172
	v_add_f32_e32 v180, v247, v180
	v_mul_f32_e32 v181, v244, v171
	v_fmac_f32_e32 v181, v245, v172
	v_fmac_f32_e32 v181, v246, v173
	v_add_f32_e32 v181, v247, v181
	v_mul_f32_e32 v174, v174, v178
	v_mul_f32_e32 v175, v175, v179
	v_mul_f32_e32 v176, v176, v180
	v_mul_f32_e32 v177, v177, v181
	v_cvt_pk_bf16_f32 v182, v174, v175
	v_cvt_pk_bf16_f32 v183, v176, v177
	ds_write_b64 v235, v[182:183] offset:0
	v_and_b32_e32 v168, 0xffff0000, v80
	v_lshlrev_b32_e32 v169, 16, v81
	v_and_b32_e32 v170, 0xffff0000, v81
	v_lshlrev_b32_e32 v171, 16, v82
	v_and_b32_e32 v172, 0xffff0000, v82
	v_lshlrev_b32_e32 v173, 16, v83
	v_mul_f32_e32 v174, v240, v168
	v_fmac_f32_e32 v174, v241, v169
	v_fmac_f32_e32 v174, v242, v170
	v_add_f32_e32 v174, v243, v174
	v_mul_f32_e32 v175, v240, v169
	v_fmac_f32_e32 v175, v241, v170
	v_fmac_f32_e32 v175, v242, v171
	v_add_f32_e32 v175, v243, v175
	v_mul_f32_e32 v176, v240, v170
	v_fmac_f32_e32 v176, v241, v171
	v_fmac_f32_e32 v176, v242, v172
	v_add_f32_e32 v176, v243, v176
	v_mul_f32_e32 v177, v240, v171
	v_fmac_f32_e32 v177, v241, v172
	v_fmac_f32_e32 v177, v242, v173
	v_add_f32_e32 v177, v243, v177
	v_mul_f32_e32 v174, v239, v174
	v_mul_f32_e32 v175, v239, v175
	v_mul_f32_e32 v176, v239, v176
	v_mul_f32_e32 v177, v239, v177
	v_fmac_f32_e32 v174, v238, v52
	v_fmac_f32_e32 v175, v238, v53
	v_fmac_f32_e32 v176, v238, v54
	v_fmac_f32_e32 v177, v238, v55
	v_and_b32_e32 v168, 0xffff0000, v84
	v_lshlrev_b32_e32 v169, 16, v85
	v_and_b32_e32 v170, 0xffff0000, v85
	v_lshlrev_b32_e32 v171, 16, v86
	v_and_b32_e32 v172, 0xffff0000, v86
	v_lshlrev_b32_e32 v173, 16, v87
	v_mul_f32_e32 v178, v244, v168
	v_fmac_f32_e32 v178, v245, v169
	v_fmac_f32_e32 v178, v246, v170
	v_add_f32_e32 v178, v247, v178
	v_mul_f32_e32 v179, v244, v169
	v_fmac_f32_e32 v179, v245, v170
	v_fmac_f32_e32 v179, v246, v171
	v_add_f32_e32 v179, v247, v179
	v_mul_f32_e32 v180, v244, v170
	v_fmac_f32_e32 v180, v245, v171
	v_fmac_f32_e32 v180, v246, v172
	v_add_f32_e32 v180, v247, v180
	v_mul_f32_e32 v181, v244, v171
	v_fmac_f32_e32 v181, v245, v172
	v_fmac_f32_e32 v181, v246, v173
	v_add_f32_e32 v181, v247, v181
	v_mul_f32_e32 v174, v174, v178
	v_mul_f32_e32 v175, v175, v179
	v_mul_f32_e32 v176, v176, v180
	v_mul_f32_e32 v177, v177, v181
	v_cvt_pk_bf16_f32 v182, v174, v175
	v_cvt_pk_bf16_f32 v183, v176, v177
	ds_write_b64 v235, v[182:183] offset:16
	v_and_b32_e32 v168, 0xffff0000, v88
	v_lshlrev_b32_e32 v169, 16, v89
	v_and_b32_e32 v170, 0xffff0000, v89
	v_lshlrev_b32_e32 v171, 16, v90
	v_and_b32_e32 v172, 0xffff0000, v90
	v_lshlrev_b32_e32 v173, 16, v91
	v_mul_f32_e32 v174, v240, v168
	v_fmac_f32_e32 v174, v241, v169
	v_fmac_f32_e32 v174, v242, v170
	v_add_f32_e32 v174, v243, v174
	v_mul_f32_e32 v175, v240, v169
	v_fmac_f32_e32 v175, v241, v170
	v_fmac_f32_e32 v175, v242, v171
	v_add_f32_e32 v175, v243, v175
	v_mul_f32_e32 v176, v240, v170
	v_fmac_f32_e32 v176, v241, v171
	v_fmac_f32_e32 v176, v242, v172
	v_add_f32_e32 v176, v243, v176
	v_mul_f32_e32 v177, v240, v171
	v_fmac_f32_e32 v177, v241, v172
	v_fmac_f32_e32 v177, v242, v173
	v_add_f32_e32 v177, v243, v177
	v_mul_f32_e32 v174, v239, v174
	v_mul_f32_e32 v175, v239, v175
	v_mul_f32_e32 v176, v239, v176
	v_mul_f32_e32 v177, v239, v177
; DI float bf2f(unsigned v) { return __uint_as_float(v << 16); }
; DI float bflo(unsigned v) { return __uint_as_float(v << 16); }
; DI float bfhi(unsigned v) { return __uint_as_float(v & 0xffff0000u); }
; DI void sconv4(const u16* row, int t4, float w0, float w1, float w2, float bias, float (&o)[4]) {
;   const uint2 v = *(const uint2*)(row + t4);
;   const float x0 = bflo(v.x), x1 = bfhi(v.x), x2 = bflo(v.y), x3 = bfhi(v.y);
;   const float xm = (t4 > 0) ? bf2f(row[t4 - 1]) : 0.f;
;   const float xp = (t4 + 4 < SEQ) ? bf2f(row[t4 + 4]) : 0.f;
;   o[0] = w0 * xm + w1 * x0 + w2 * x1 + bias;
;   o[1] = w0 * x0 + w1 * x1 + w2 * x2 + bias;
;   o[2] = w0 * x1 + w1 * x2 + w2 * x3 + bias;
;   o[3] = w0 * x2 + w1 * x3 + w2 * xp + bias;
; }
; DI void hyena_item(const P& p, int l, int c, char* smem) {
;     ...
; #pragma unroll
;     for (int I = 0; I < 4; ++I)
; #pragma unroll
;       for (int rq = 0; rq < 4; ++rq) {
;         const int bq = 32 * I + 8 * rq + 4 * g;
;         const int t4 = 128 * a + bq;
;         float pv[4], px[4];
;         sconv4(rowv, t4, v0, v1, v2, vb, pv);
;         sconv4(rowx, t4, x0, x1, x2, xb, px);
;         float zz[4];
; #pragma unroll
;         for (int j = 0; j < 4; ++j) zz[j] = px[j] * (acc[I][4 * rq + j] * invn0 + pv[j] * d0);
;         uint2 ov; ov.x = pack2(zz[0], zz[1]); ov.y = pack2(zz[2], zz[3]);
;         *(uint2*)(U + (bt * 64 + a) * 136 + bq) = ov;
;       }
	v_fmac_f32_e32 v174, v238, v56
	v_fmac_f32_e32 v175, v238, v57
	v_fmac_f32_e32 v176, v238, v58
	v_fmac_f32_e32 v177, v238, v59
	v_and_b32_e32 v168, 0xffff0000, v92
	v_lshlrev_b32_e32 v169, 16, v93
	v_and_b32_e32 v170, 0xffff0000, v93
	v_lshlrev_b32_e32 v171, 16, v94
	v_and_b32_e32 v172, 0xffff0000, v94
	v_lshlrev_b32_e32 v173, 16, v95
	v_mul_f32_e32 v178, v244, v168
	v_fmac_f32_e32 v178, v245, v169
	v_fmac_f32_e32 v178, v246, v170
	v_add_f32_e32 v178, v247, v178
	v_mul_f32_e32 v179, v244, v169
	v_fmac_f32_e32 v179, v245, v170
	v_fmac_f32_e32 v179, v246, v171
	v_add_f32_e32 v179, v247, v179
	v_mul_f32_e32 v180, v244, v170
	v_fmac_f32_e32 v180, v245, v171
	v_fmac_f32_e32 v180, v246, v172
	v_add_f32_e32 v180, v247, v180
	v_mul_f32_e32 v181, v244, v171
	v_fmac_f32_e32 v181, v245, v172
	v_fmac_f32_e32 v181, v246, v173
	v_add_f32_e32 v181, v247, v181
	v_mul_f32_e32 v174, v174, v178
	v_mul_f32_e32 v175, v175, v179
	v_mul_f32_e32 v176, v176, v180
	v_mul_f32_e32 v177, v177, v181
	v_cvt_pk_bf16_f32 v182, v174, v175
	v_cvt_pk_bf16_f32 v183, v176, v177
	ds_write_b64 v235, v[182:183] offset:32
	v_and_b32_e32 v168, 0xffff0000, v96
	v_lshlrev_b32_e32 v169, 16, v97
	v_and_b32_e32 v170, 0xffff0000, v97
	v_lshlrev_b32_e32 v171, 16, v98
	v_and_b32_e32 v172, 0xffff0000, v98
	v_lshlrev_b32_e32 v173, 16, v99
	v_mul_f32_e32 v174, v240, v168
	v_fmac_f32_e32 v174, v241, v169
	v_fmac_f32_e32 v174, v242, v170
	v_add_f32_e32 v174, v243, v174
	v_mul_f32_e32 v175, v240, v169
	v_fmac_f32_e32 v175, v241, v170
	v_fmac_f32_e32 v175, v242, v171
	v_add_f32_e32 v175, v243, v175
	v_mul_f32_e32 v176, v240, v170
	v_fmac_f32_e32 v176, v241, v171
	v_fmac_f32_e32 v176, v242, v172
	v_add_f32_e32 v176, v243, v176
	v_mul_f32_e32 v177, v240, v171
	v_fmac_f32_e32 v177, v241, v172
	v_fmac_f32_e32 v177, v242, v173
	v_add_f32_e32 v177, v243, v177
	v_mul_f32_e32 v174, v239, v174
	v_mul_f32_e32 v175, v239, v175
	v_mul_f32_e32 v176, v239, v176
	v_mul_f32_e32 v177, v239, v177
	v_fmac_f32_e32 v174, v238, v60
	v_fmac_f32_e32 v175, v238, v61
	v_fmac_f32_e32 v176, v238, v62
	v_fmac_f32_e32 v177, v238, v63
	v_and_b32_e32 v168, 0xffff0000, v100
	v_lshlrev_b32_e32 v169, 16, v101
	v_and_b32_e32 v170, 0xffff0000, v101
	v_lshlrev_b32_e32 v171, 16, v102
	v_and_b32_e32 v172, 0xffff0000, v102
	v_lshlrev_b32_e32 v173, 16, v103
	v_mul_f32_e32 v178, v244, v168
	v_fmac_f32_e32 v178, v245, v169
	v_fmac_f32_e32 v178, v246, v170
	v_add_f32_e32 v178, v247, v178
	v_mul_f32_e32 v179, v244, v169
	v_fmac_f32_e32 v179, v245, v170
	v_fmac_f32_e32 v179, v246, v171
	v_add_f32_e32 v179, v247, v179
	v_mul_f32_e32 v180, v244, v170
	v_fmac_f32_e32 v180, v245, v171
	v_fmac_f32_e32 v180, v246, v172
	v_add_f32_e32 v180, v247, v180
	v_mul_f32_e32 v181, v244, v171
	v_fmac_f32_e32 v181, v245, v172
	v_fmac_f32_e32 v181, v246, v173
	v_add_f32_e32 v181, v247, v181
	v_mul_f32_e32 v174, v174, v178
	v_mul_f32_e32 v175, v175, v179
	v_mul_f32_e32 v176, v176, v180
	v_mul_f32_e32 v177, v177, v181
	v_cvt_pk_bf16_f32 v182, v174, v175
	v_cvt_pk_bf16_f32 v183, v176, v177
	ds_write_b64 v235, v[182:183] offset:48
	global_load_dwordx4 v[136:139], v234, s[100:101] offset:128
	global_load_dwordx4 v[140:143], v234, s[98:99] offset:128
	global_load_dwordx4 v[144:147], v234, s[100:101] offset:144
	global_load_dwordx4 v[148:151], v234, s[98:99] offset:144
	global_load_dwordx4 v[152:155], v234, s[100:101] offset:160
	global_load_dwordx4 v[156:159], v234, s[98:99] offset:160
	global_load_dwordx4 v[160:163], v234, s[100:101] offset:176
	global_load_dwordx4 v[164:167], v234, s[98:99] offset:176
	s_waitcnt vmcnt(8)
	v_and_b32_e32 v168, 0xffff0000, v104
	v_lshlrev_b32_e32 v169, 16, v105
	v_and_b32_e32 v170, 0xffff0000, v105
	v_lshlrev_b32_e32 v171, 16, v106
	v_and_b32_e32 v172, 0xffff0000, v106
	v_lshlrev_b32_e32 v173, 16, v107
	v_mul_f32_e32 v174, v240, v168
	v_fmac_f32_e32 v174, v241, v169
	v_fmac_f32_e32 v174, v242, v170
	v_add_f32_e32 v174, v243, v174
	v_mul_f32_e32 v175, v240, v169
	v_fmac_f32_e32 v175, v241, v170
	v_fmac_f32_e32 v175, v242, v171
	v_add_f32_e32 v175, v243, v175
	v_mul_f32_e32 v176, v240, v170
	v_fmac_f32_e32 v176, v241, v171
	v_fmac_f32_e32 v176, v242, v172
	v_add_f32_e32 v176, v243, v176
	v_mul_f32_e32 v177, v240, v171
	v_fmac_f32_e32 v177, v241, v172
	v_fmac_f32_e32 v177, v242, v173
	v_add_f32_e32 v177, v243, v177
	v_mul_f32_e32 v174, v239, v174
	v_mul_f32_e32 v175, v239, v175
	v_mul_f32_e32 v176, v239, v176
	v_mul_f32_e32 v177, v239, v177
	v_fmac_f32_e32 v174, v238, v32
	v_fmac_f32_e32 v175, v238, v33
	v_fmac_f32_e32 v176, v238, v34
	v_fmac_f32_e32 v177, v238, v35
	v_and_b32_e32 v168, 0xffff0000, v108
	v_lshlrev_b32_e32 v169, 16, v109
	v_and_b32_e32 v170, 0xffff0000, v109
	v_lshlrev_b32_e32 v171, 16, v110
	v_and_b32_e32 v172, 0xffff0000, v110
	v_lshlrev_b32_e32 v173, 16, v111
	v_mul_f32_e32 v178, v244, v168
	v_fmac_f32_e32 v178, v245, v169
	v_fmac_f32_e32 v178, v246, v170
	v_add_f32_e32 v178, v247, v178
	v_mul_f32_e32 v179, v244, v169
	v_fmac_f32_e32 v179, v245, v170
	v_fmac_f32_e32 v179, v246, v171
	v_add_f32_e32 v179, v247, v179
	v_mul_f32_e32 v180, v244, v170
	v_fmac_f32_e32 v180, v245, v171
	v_fmac_f32_e32 v180, v246, v172
	v_add_f32_e32 v180, v247, v180
	v_mul_f32_e32 v181, v244, v171
	v_fmac_f32_e32 v181, v245, v172
	v_fmac_f32_e32 v181, v246, v173
	v_add_f32_e32 v181, v247, v181
	v_mul_f32_e32 v174, v174, v178
	v_mul_f32_e32 v175, v175, v179
	v_mul_f32_e32 v176, v176, v180
	v_mul_f32_e32 v177, v177, v181
	v_cvt_pk_bf16_f32 v182, v174, v175
	v_cvt_pk_bf16_f32 v183, v176, v177
	ds_write_b64 v235, v[182:183] offset:64
	v_and_b32_e32 v168, 0xffff0000, v112
	v_lshlrev_b32_e32 v169, 16, v113
	v_and_b32_e32 v170, 0xffff0000, v113
; DI float bf2f(unsigned v) { return __uint_as_float(v << 16); }
; DI float bflo(unsigned v) { return __uint_as_float(v << 16); }
; DI float bfhi(unsigned v) { return __uint_as_float(v & 0xffff0000u); }
; DI void sconv4(const u16* row, int t4, float w0, float w1, float w2, float bias, float (&o)[4]) {
;   const uint2 v = *(const uint2*)(row + t4);
;   const float x0 = bflo(v.x), x1 = bfhi(v.x), x2 = bflo(v.y), x3 = bfhi(v.y);
;   const float xm = (t4 > 0) ? bf2f(row[t4 - 1]) : 0.f;
;   const float xp = (t4 + 4 < SEQ) ? bf2f(row[t4 + 4]) : 0.f;
;   o[0] = w0 * xm + w1 * x0 + w2 * x1 + bias;
;   o[1] = w0 * x0 + w1 * x1 + w2 * x2 + bias;
;   o[2] = w0 * x1 + w1 * x2 + w2 * x3 + bias;
;   o[3] = w0 * x2 + w1 * x3 + w2 * xp + bias;
; }
; DI void hyena_item(const P& p, int l, int c, char* smem) {
;     ...
; #pragma unroll
;     for (int I = 0; I < 4; ++I)
; #pragma unroll
;       for (int rq = 0; rq < 4; ++rq) {
;         const int bq = 32 * I + 8 * rq + 4 * g;
;         const int t4 = 128 * a + bq;
;         float pv[4], px[4];
;         sconv4(rowv, t4, v0, v1, v2, vb, pv);
;         sconv4(rowx, t4, x0, x1, x2, xb, px);
;         float zz[4];
; #pragma unroll
;         for (int j = 0; j < 4; ++j) zz[j] = px[j] * (acc[I][4 * rq + j] * invn0 + pv[j] * d0);
;         uint2 ov; ov.x = pack2(zz[0], zz[1]); ov.y = pack2(zz[2], zz[3]);
;         *(uint2*)(U + (bt * 64 + a) * 136 + bq) = ov;
;       }
	v_lshlrev_b32_e32 v171, 16, v114
	v_and_b32_e32 v172, 0xffff0000, v114
	v_lshlrev_b32_e32 v173, 16, v115
	v_mul_f32_e32 v174, v240, v168
	v_fmac_f32_e32 v174, v241, v169
	v_fmac_f32_e32 v174, v242, v170
	v_add_f32_e32 v174, v243, v174
	v_mul_f32_e32 v175, v240, v169
	v_fmac_f32_e32 v175, v241, v170
	v_fmac_f32_e32 v175, v242, v171
	v_add_f32_e32 v175, v243, v175
	v_mul_f32_e32 v176, v240, v170
	v_fmac_f32_e32 v176, v241, v171
	v_fmac_f32_e32 v176, v242, v172
	v_add_f32_e32 v176, v243, v176
	v_mul_f32_e32 v177, v240, v171
	v_fmac_f32_e32 v177, v241, v172
	v_fmac_f32_e32 v177, v242, v173
	v_add_f32_e32 v177, v243, v177
	v_mul_f32_e32 v174, v239, v174
	v_mul_f32_e32 v175, v239, v175
	v_mul_f32_e32 v176, v239, v176
	v_mul_f32_e32 v177, v239, v177
	v_fmac_f32_e32 v174, v238, v36
	v_fmac_f32_e32 v175, v238, v37
	v_fmac_f32_e32 v176, v238, v38
	v_fmac_f32_e32 v177, v238, v39
	v_and_b32_e32 v168, 0xffff0000, v116
	v_lshlrev_b32_e32 v169, 16, v117
	v_and_b32_e32 v170, 0xffff0000, v117
	v_lshlrev_b32_e32 v171, 16, v118
	v_and_b32_e32 v172, 0xffff0000, v118
	v_lshlrev_b32_e32 v173, 16, v119
	v_mul_f32_e32 v178, v244, v168
	v_fmac_f32_e32 v178, v245, v169
	v_fmac_f32_e32 v178, v246, v170
	v_add_f32_e32 v178, v247, v178
	v_mul_f32_e32 v179, v244, v169
	v_fmac_f32_e32 v179, v245, v170
	v_fmac_f32_e32 v179, v246, v171
	v_add_f32_e32 v179, v247, v179
	v_mul_f32_e32 v180, v244, v170
	v_fmac_f32_e32 v180, v245, v171
	v_fmac_f32_e32 v180, v246, v172
	v_add_f32_e32 v180, v247, v180
	v_mul_f32_e32 v181, v244, v171
	v_fmac_f32_e32 v181, v245, v172
	v_fmac_f32_e32 v181, v246, v173
	v_add_f32_e32 v181, v247, v181
	v_mul_f32_e32 v174, v174, v178
	v_mul_f32_e32 v175, v175, v179
	v_mul_f32_e32 v176, v176, v180
	v_mul_f32_e32 v177, v177, v181
	v_cvt_pk_bf16_f32 v182, v174, v175
	v_cvt_pk_bf16_f32 v183, v176, v177
	ds_write_b64 v235, v[182:183] offset:80
	v_and_b32_e32 v168, 0xffff0000, v120
	v_lshlrev_b32_e32 v169, 16, v121
	v_and_b32_e32 v170, 0xffff0000, v121
	v_lshlrev_b32_e32 v171, 16, v122
	v_and_b32_e32 v172, 0xffff0000, v122
	v_lshlrev_b32_e32 v173, 16, v123
	v_mul_f32_e32 v174, v240, v168
	v_fmac_f32_e32 v174, v241, v169
	v_fmac_f32_e32 v174, v242, v170
	v_add_f32_e32 v174, v243, v174
	v_mul_f32_e32 v175, v240, v169
	v_fmac_f32_e32 v175, v241, v170
	v_fmac_f32_e32 v175, v242, v171
	v_add_f32_e32 v175, v243, v175
	v_mul_f32_e32 v176, v240, v170
	v_fmac_f32_e32 v176, v241, v171
	v_fmac_f32_e32 v176, v242, v172
	v_add_f32_e32 v176, v243, v176
	v_mul_f32_e32 v177, v240, v171
	v_fmac_f32_e32 v177, v241, v172
	v_fmac_f32_e32 v177, v242, v173
	v_add_f32_e32 v177, v243, v177
	v_mul_f32_e32 v174, v239, v174
	v_mul_f32_e32 v175, v239, v175
	v_mul_f32_e32 v176, v239, v176
	v_mul_f32_e32 v177, v239, v177
	v_fmac_f32_e32 v174, v238, v40
	v_fmac_f32_e32 v175, v238, v41
	v_fmac_f32_e32 v176, v238, v42
	v_fmac_f32_e32 v177, v238, v43
	v_and_b32_e32 v168, 0xffff0000, v124
	v_lshlrev_b32_e32 v169, 16, v125
	v_and_b32_e32 v170, 0xffff0000, v125
	v_lshlrev_b32_e32 v171, 16, v126
	v_and_b32_e32 v172, 0xffff0000, v126
	v_lshlrev_b32_e32 v173, 16, v127
	v_mul_f32_e32 v178, v244, v168
	v_fmac_f32_e32 v178, v245, v169
	v_fmac_f32_e32 v178, v246, v170
	v_add_f32_e32 v178, v247, v178
	v_mul_f32_e32 v179, v244, v169
	v_fmac_f32_e32 v179, v245, v170
	v_fmac_f32_e32 v179, v246, v171
	v_add_f32_e32 v179, v247, v179
	v_mul_f32_e32 v180, v244, v170
	v_fmac_f32_e32 v180, v245, v171
	v_fmac_f32_e32 v180, v246, v172
	v_add_f32_e32 v180, v247, v180
	v_mul_f32_e32 v181, v244, v171
	v_fmac_f32_e32 v181, v245, v172
	v_fmac_f32_e32 v181, v246, v173
	v_add_f32_e32 v181, v247, v181
	v_mul_f32_e32 v174, v174, v178
	v_mul_f32_e32 v175, v175, v179
	v_mul_f32_e32 v176, v176, v180
	v_mul_f32_e32 v177, v177, v181
	v_cvt_pk_bf16_f32 v182, v174, v175
	v_cvt_pk_bf16_f32 v183, v176, v177
	ds_write_b64 v235, v[182:183] offset:96
	v_and_b32_e32 v168, 0xffff0000, v128
	v_lshlrev_b32_e32 v169, 16, v129
	v_and_b32_e32 v170, 0xffff0000, v129
	v_lshlrev_b32_e32 v171, 16, v130
	v_and_b32_e32 v172, 0xffff0000, v130
	v_lshlrev_b32_e32 v173, 16, v131
	v_mul_f32_e32 v174, v240, v168
	v_fmac_f32_e32 v174, v241, v169
	v_fmac_f32_e32 v174, v242, v170
	v_add_f32_e32 v174, v243, v174
	v_mul_f32_e32 v175, v240, v169
	v_fmac_f32_e32 v175, v241, v170
	v_fmac_f32_e32 v175, v242, v171
	v_add_f32_e32 v175, v243, v175
	v_mul_f32_e32 v176, v240, v170
	v_fmac_f32_e32 v176, v241, v171
	v_fmac_f32_e32 v176, v242, v172
	v_add_f32_e32 v176, v243, v176
	v_mul_f32_e32 v177, v240, v171
	v_fmac_f32_e32 v177, v241, v172
	v_fmac_f32_e32 v177, v242, v173
	v_add_f32_e32 v177, v243, v177
	v_mul_f32_e32 v174, v239, v174
	v_mul_f32_e32 v175, v239, v175
	v_mul_f32_e32 v176, v239, v176
	v_mul_f32_e32 v177, v239, v177
	v_fmac_f32_e32 v174, v238, v44
	v_fmac_f32_e32 v175, v238, v45
	v_fmac_f32_e32 v176, v238, v46
	v_fmac_f32_e32 v177, v238, v47
	v_and_b32_e32 v168, 0xffff0000, v132
	v_lshlrev_b32_e32 v169, 16, v133
	v_and_b32_e32 v170, 0xffff0000, v133
	v_lshlrev_b32_e32 v171, 16, v134
	v_and_b32_e32 v172, 0xffff0000, v134
	v_lshlrev_b32_e32 v173, 16, v135
	v_mul_f32_e32 v178, v244, v168
	v_fmac_f32_e32 v178, v245, v169
	v_fmac_f32_e32 v178, v246, v170
	v_add_f32_e32 v178, v247, v178
	v_mul_f32_e32 v179, v244, v169
	v_fmac_f32_e32 v179, v245, v170
	v_fmac_f32_e32 v179, v246, v171
	v_add_f32_e32 v179, v247, v179
	v_mul_f32_e32 v180, v244, v170
	v_fmac_f32_e32 v180, v245, v171
	v_fmac_f32_e32 v180, v246, v172
	v_add_f32_e32 v180, v247, v180
	v_mul_f32_e32 v181, v244, v171
	v_fmac_f32_e32 v181, v245, v172
	v_fmac_f32_e32 v181, v246, v173
	v_add_f32_e32 v181, v247, v181
	v_mul_f32_e32 v174, v174, v178
	v_mul_f32_e32 v175, v175, v179
	v_mul_f32_e32 v176, v176, v180
	v_mul_f32_e32 v177, v177, v181
	v_cvt_pk_bf16_f32 v182, v174, v175
	v_cvt_pk_bf16_f32 v183, v176, v177
	ds_write_b64 v235, v[182:183] offset:112
	global_load_dwordx4 v[72:75], v234, s[100:101] offset:192
	global_load_dwordx4 v[76:79], v234, s[98:99] offset:192
	global_load_dwordx4 v[80:83], v234, s[100:101] offset:208
	global_load_dwordx4 v[84:87], v234, s[98:99] offset:208
	global_load_dwordx4 v[88:91], v234, s[100:101] offset:224
	global_load_dwordx4 v[92:95], v234, s[98:99] offset:224
	global_load_dwordx4 v[96:99], v234, s[100:101] offset:240
	global_load_dwordx4 v[100:103], v234, s[98:99] offset:240
	s_waitcnt vmcnt(8)
; DI float bf2f(unsigned v) { return __uint_as_float(v << 16); }
; DI float bflo(unsigned v) { return __uint_as_float(v << 16); }
; DI float bfhi(unsigned v) { return __uint_as_float(v & 0xffff0000u); }
; DI void sconv4(const u16* row, int t4, float w0, float w1, float w2, float bias, float (&o)[4]) {
;   const uint2 v = *(const uint2*)(row + t4);
;   const float x0 = bflo(v.x), x1 = bfhi(v.x), x2 = bflo(v.y), x3 = bfhi(v.y);
;   const float xm = (t4 > 0) ? bf2f(row[t4 - 1]) : 0.f;
;   const float xp = (t4 + 4 < SEQ) ? bf2f(row[t4 + 4]) : 0.f;
;   o[0] = w0 * xm + w1 * x0 + w2 * x1 + bias;
;   o[1] = w0 * x0 + w1 * x1 + w2 * x2 + bias;
;   o[2] = w0 * x1 + w1 * x2 + w2 * x3 + bias;
;   o[3] = w0 * x2 + w1 * x3 + w2 * xp + bias;
; }
; DI void hyena_item(const P& p, int l, int c, char* smem) {
;     ...
; #pragma unroll
;     for (int I = 0; I < 4; ++I)
; #pragma unroll
;       for (int rq = 0; rq < 4; ++rq) {
;         const int bq = 32 * I + 8 * rq + 4 * g;
;         const int t4 = 128 * a + bq;
;         float pv[4], px[4];
;         sconv4(rowv, t4, v0, v1, v2, vb, pv);
;         sconv4(rowx, t4, x0, x1, x2, xb, px);
;         float zz[4];
; #pragma unroll
;         for (int j = 0; j < 4; ++j) zz[j] = px[j] * (acc[I][4 * rq + j] * invn0 + pv[j] * d0);
;         uint2 ov; ov.x = pack2(zz[0], zz[1]); ov.y = pack2(zz[2], zz[3]);
;         *(uint2*)(U + (bt * 64 + a) * 136 + bq) = ov;
;       }
	v_and_b32_e32 v168, 0xffff0000, v136
	v_lshlrev_b32_e32 v169, 16, v137
	v_and_b32_e32 v170, 0xffff0000, v137
	v_lshlrev_b32_e32 v171, 16, v138
	v_and_b32_e32 v172, 0xffff0000, v138
	v_lshlrev_b32_e32 v173, 16, v139
	v_mul_f32_e32 v174, v240, v168
	v_fmac_f32_e32 v174, v241, v169
	v_fmac_f32_e32 v174, v242, v170
	v_add_f32_e32 v174, v243, v174
	v_mul_f32_e32 v175, v240, v169
	v_fmac_f32_e32 v175, v241, v170
	v_fmac_f32_e32 v175, v242, v171
	v_add_f32_e32 v175, v243, v175
	v_mul_f32_e32 v176, v240, v170
	v_fmac_f32_e32 v176, v241, v171
	v_fmac_f32_e32 v176, v242, v172
	v_add_f32_e32 v176, v243, v176
	v_mul_f32_e32 v177, v240, v171
	v_fmac_f32_e32 v177, v241, v172
	v_fmac_f32_e32 v177, v242, v173
	v_add_f32_e32 v177, v243, v177
	v_mul_f32_e32 v174, v239, v174
	v_mul_f32_e32 v175, v239, v175
	v_mul_f32_e32 v176, v239, v176
	v_mul_f32_e32 v177, v239, v177
	v_fmac_f32_e32 v174, v238, v16
	v_fmac_f32_e32 v175, v238, v17
	v_fmac_f32_e32 v176, v238, v18
	v_fmac_f32_e32 v177, v238, v19
	v_and_b32_e32 v168, 0xffff0000, v140
	v_lshlrev_b32_e32 v169, 16, v141
	v_and_b32_e32 v170, 0xffff0000, v141
	v_lshlrev_b32_e32 v171, 16, v142
	v_and_b32_e32 v172, 0xffff0000, v142
	v_lshlrev_b32_e32 v173, 16, v143
	v_mul_f32_e32 v178, v244, v168
	v_fmac_f32_e32 v178, v245, v169
	v_fmac_f32_e32 v178, v246, v170
	v_add_f32_e32 v178, v247, v178
	v_mul_f32_e32 v179, v244, v169
	v_fmac_f32_e32 v179, v245, v170
	v_fmac_f32_e32 v179, v246, v171
	v_add_f32_e32 v179, v247, v179
	v_mul_f32_e32 v180, v244, v170
	v_fmac_f32_e32 v180, v245, v171
	v_fmac_f32_e32 v180, v246, v172
	v_add_f32_e32 v180, v247, v180
	v_mul_f32_e32 v181, v244, v171
	v_fmac_f32_e32 v181, v245, v172
	v_fmac_f32_e32 v181, v246, v173
	v_add_f32_e32 v181, v247, v181
	v_mul_f32_e32 v174, v174, v178
	v_mul_f32_e32 v175, v175, v179
	v_mul_f32_e32 v176, v176, v180
	v_mul_f32_e32 v177, v177, v181
	v_cvt_pk_bf16_f32 v182, v174, v175
	v_cvt_pk_bf16_f32 v183, v176, v177
	ds_write_b64 v235, v[182:183] offset:128
	v_and_b32_e32 v168, 0xffff0000, v144
	v_lshlrev_b32_e32 v169, 16, v145
	v_and_b32_e32 v170, 0xffff0000, v145
	v_lshlrev_b32_e32 v171, 16, v146
	v_and_b32_e32 v172, 0xffff0000, v146
	v_lshlrev_b32_e32 v173, 16, v147
	v_mul_f32_e32 v174, v240, v168
	v_fmac_f32_e32 v174, v241, v169
	v_fmac_f32_e32 v174, v242, v170
	v_add_f32_e32 v174, v243, v174
	v_mul_f32_e32 v175, v240, v169
	v_fmac_f32_e32 v175, v241, v170
	v_fmac_f32_e32 v175, v242, v171
	v_add_f32_e32 v175, v243, v175
	v_mul_f32_e32 v176, v240, v170
	v_fmac_f32_e32 v176, v241, v171
	v_fmac_f32_e32 v176, v242, v172
	v_add_f32_e32 v176, v243, v176
	v_mul_f32_e32 v177, v240, v171
	v_fmac_f32_e32 v177, v241, v172
	v_fmac_f32_e32 v177, v242, v173
	v_add_f32_e32 v177, v243, v177
	v_mul_f32_e32 v174, v239, v174
	v_mul_f32_e32 v175, v239, v175
	v_mul_f32_e32 v176, v239, v176
	v_mul_f32_e32 v177, v239, v177
	v_fmac_f32_e32 v174, v238, v20
	v_fmac_f32_e32 v175, v238, v21
	v_fmac_f32_e32 v176, v238, v22
	v_fmac_f32_e32 v177, v238, v23
	v_and_b32_e32 v168, 0xffff0000, v148
	v_lshlrev_b32_e32 v169, 16, v149
	v_and_b32_e32 v170, 0xffff0000, v149
	v_lshlrev_b32_e32 v171, 16, v150
	v_and_b32_e32 v172, 0xffff0000, v150
	v_lshlrev_b32_e32 v173, 16, v151
	v_mul_f32_e32 v178, v244, v168
	v_fmac_f32_e32 v178, v245, v169
	v_fmac_f32_e32 v178, v246, v170
	v_add_f32_e32 v178, v247, v178
	v_mul_f32_e32 v179, v244, v169
	v_fmac_f32_e32 v179, v245, v170
	v_fmac_f32_e32 v179, v246, v171
	v_add_f32_e32 v179, v247, v179
	v_mul_f32_e32 v180, v244, v170
	v_fmac_f32_e32 v180, v245, v171
	v_fmac_f32_e32 v180, v246, v172
	v_add_f32_e32 v180, v247, v180
	v_mul_f32_e32 v181, v244, v171
	v_fmac_f32_e32 v181, v245, v172
	v_fmac_f32_e32 v181, v246, v173
	v_add_f32_e32 v181, v247, v181
	v_mul_f32_e32 v174, v174, v178
	v_mul_f32_e32 v175, v175, v179
	v_mul_f32_e32 v176, v176, v180
	v_mul_f32_e32 v177, v177, v181
	v_cvt_pk_bf16_f32 v182, v174, v175
	v_cvt_pk_bf16_f32 v183, v176, v177
	ds_write_b64 v235, v[182:183] offset:144
	v_and_b32_e32 v168, 0xffff0000, v152
	v_lshlrev_b32_e32 v169, 16, v153
	v_and_b32_e32 v170, 0xffff0000, v153
	v_lshlrev_b32_e32 v171, 16, v154
	v_and_b32_e32 v172, 0xffff0000, v154
	v_lshlrev_b32_e32 v173, 16, v155
	v_mul_f32_e32 v174, v240, v168
	v_fmac_f32_e32 v174, v241, v169
	v_fmac_f32_e32 v174, v242, v170
	v_add_f32_e32 v174, v243, v174
	v_mul_f32_e32 v175, v240, v169
	v_fmac_f32_e32 v175, v241, v170
	v_fmac_f32_e32 v175, v242, v171
	v_add_f32_e32 v175, v243, v175
	v_mul_f32_e32 v176, v240, v170
	v_fmac_f32_e32 v176, v241, v171
	v_fmac_f32_e32 v176, v242, v172
	v_add_f32_e32 v176, v243, v176
	v_mul_f32_e32 v177, v240, v171
	v_fmac_f32_e32 v177, v241, v172
	v_fmac_f32_e32 v177, v242, v173
	v_add_f32_e32 v177, v243, v177
	v_mul_f32_e32 v174, v239, v174
	v_mul_f32_e32 v175, v239, v175
	v_mul_f32_e32 v176, v239, v176
	v_mul_f32_e32 v177, v239, v177
	v_fmac_f32_e32 v174, v238, v24
	v_fmac_f32_e32 v175, v238, v25
	v_fmac_f32_e32 v176, v238, v26
	v_fmac_f32_e32 v177, v238, v27
	v_and_b32_e32 v168, 0xffff0000, v156
	v_lshlrev_b32_e32 v169, 16, v157
	v_and_b32_e32 v170, 0xffff0000, v157
	v_lshlrev_b32_e32 v171, 16, v158
	v_and_b32_e32 v172, 0xffff0000, v158
	v_lshlrev_b32_e32 v173, 16, v159
	v_mul_f32_e32 v178, v244, v168
	v_fmac_f32_e32 v178, v245, v169
	v_fmac_f32_e32 v178, v246, v170
	v_add_f32_e32 v178, v247, v178
	v_mul_f32_e32 v179, v244, v169
	v_fmac_f32_e32 v179, v245, v170
	v_fmac_f32_e32 v179, v246, v171
	v_add_f32_e32 v179, v247, v179
	v_mul_f32_e32 v180, v244, v170
	v_fmac_f32_e32 v180, v245, v171
	v_fmac_f32_e32 v180, v246, v172
	v_add_f32_e32 v180, v247, v180
	v_mul_f32_e32 v181, v244, v171
	v_fmac_f32_e32 v181, v245, v172
	v_fmac_f32_e32 v181, v246, v173
; DI float bf2f(unsigned v) { return __uint_as_float(v << 16); }
; DI float bflo(unsigned v) { return __uint_as_float(v << 16); }
; DI float bfhi(unsigned v) { return __uint_as_float(v & 0xffff0000u); }
; DI void sconv4(const u16* row, int t4, float w0, float w1, float w2, float bias, float (&o)[4]) {
;   const uint2 v = *(const uint2*)(row + t4);
;   const float x0 = bflo(v.x), x1 = bfhi(v.x), x2 = bflo(v.y), x3 = bfhi(v.y);
;   const float xm = (t4 > 0) ? bf2f(row[t4 - 1]) : 0.f;
;   const float xp = (t4 + 4 < SEQ) ? bf2f(row[t4 + 4]) : 0.f;
;   o[0] = w0 * xm + w1 * x0 + w2 * x1 + bias;
;   o[1] = w0 * x0 + w1 * x1 + w2 * x2 + bias;
;   o[2] = w0 * x1 + w1 * x2 + w2 * x3 + bias;
;   o[3] = w0 * x2 + w1 * x3 + w2 * xp + bias;
; }
; DI void hyena_item(const P& p, int l, int c, char* smem) {
;     ...
; #pragma unroll
;     for (int I = 0; I < 4; ++I)
; #pragma unroll
;       for (int rq = 0; rq < 4; ++rq) {
;         const int bq = 32 * I + 8 * rq + 4 * g;
;         const int t4 = 128 * a + bq;
;         float pv[4], px[4];
;         sconv4(rowv, t4, v0, v1, v2, vb, pv);
;         sconv4(rowx, t4, x0, x1, x2, xb, px);
;         float zz[4];
; #pragma unroll
;         for (int j = 0; j < 4; ++j) zz[j] = px[j] * (acc[I][4 * rq + j] * invn0 + pv[j] * d0);
;         uint2 ov; ov.x = pack2(zz[0], zz[1]); ov.y = pack2(zz[2], zz[3]);
;         *(uint2*)(U + (bt * 64 + a) * 136 + bq) = ov;
;       }
	v_add_f32_e32 v181, v247, v181
	v_mul_f32_e32 v174, v174, v178
	v_mul_f32_e32 v175, v175, v179
	v_mul_f32_e32 v176, v176, v180
	v_mul_f32_e32 v177, v177, v181
	v_cvt_pk_bf16_f32 v182, v174, v175
	v_cvt_pk_bf16_f32 v183, v176, v177
	ds_write_b64 v235, v[182:183] offset:160
	v_and_b32_e32 v168, 0xffff0000, v160
	v_lshlrev_b32_e32 v169, 16, v161
	v_and_b32_e32 v170, 0xffff0000, v161
	v_lshlrev_b32_e32 v171, 16, v162
	v_and_b32_e32 v172, 0xffff0000, v162
	v_lshlrev_b32_e32 v173, 16, v163
	v_mul_f32_e32 v174, v240, v168
	v_fmac_f32_e32 v174, v241, v169
	v_fmac_f32_e32 v174, v242, v170
	v_add_f32_e32 v174, v243, v174
	v_mul_f32_e32 v175, v240, v169
	v_fmac_f32_e32 v175, v241, v170
	v_fmac_f32_e32 v175, v242, v171
	v_add_f32_e32 v175, v243, v175
	v_mul_f32_e32 v176, v240, v170
	v_fmac_f32_e32 v176, v241, v171
	v_fmac_f32_e32 v176, v242, v172
	v_add_f32_e32 v176, v243, v176
	v_mul_f32_e32 v177, v240, v171
	v_fmac_f32_e32 v177, v241, v172
	v_fmac_f32_e32 v177, v242, v173
	v_add_f32_e32 v177, v243, v177
	v_mul_f32_e32 v174, v239, v174
	v_mul_f32_e32 v175, v239, v175
	v_mul_f32_e32 v176, v239, v176
	v_mul_f32_e32 v177, v239, v177
	v_fmac_f32_e32 v174, v238, v28
	v_fmac_f32_e32 v175, v238, v29
	v_fmac_f32_e32 v176, v238, v30
	v_fmac_f32_e32 v177, v238, v31
	v_and_b32_e32 v168, 0xffff0000, v164
	v_lshlrev_b32_e32 v169, 16, v165
	v_and_b32_e32 v170, 0xffff0000, v165
	v_lshlrev_b32_e32 v171, 16, v166
	v_and_b32_e32 v172, 0xffff0000, v166
	v_lshlrev_b32_e32 v173, 16, v167
	v_mul_f32_e32 v178, v244, v168
	v_fmac_f32_e32 v178, v245, v169
	v_fmac_f32_e32 v178, v246, v170
	v_add_f32_e32 v178, v247, v178
	v_mul_f32_e32 v179, v244, v169
	v_fmac_f32_e32 v179, v245, v170
	v_fmac_f32_e32 v179, v246, v171
	v_add_f32_e32 v179, v247, v179
	v_mul_f32_e32 v180, v244, v170
	v_fmac_f32_e32 v180, v245, v171
	v_fmac_f32_e32 v180, v246, v172
	v_add_f32_e32 v180, v247, v180
	v_mul_f32_e32 v181, v244, v171
	v_fmac_f32_e32 v181, v245, v172
	v_fmac_f32_e32 v181, v246, v173
	v_add_f32_e32 v181, v247, v181
	v_mul_f32_e32 v174, v174, v178
	v_mul_f32_e32 v175, v175, v179
	v_mul_f32_e32 v176, v176, v180
	v_mul_f32_e32 v177, v177, v181
	v_cvt_pk_bf16_f32 v182, v174, v175
	v_cvt_pk_bf16_f32 v183, v176, v177
	ds_write_b64 v235, v[182:183] offset:176
	s_waitcnt vmcnt(0)
	v_and_b32_e32 v168, 0xffff0000, v72
	v_lshlrev_b32_e32 v169, 16, v73
	v_and_b32_e32 v170, 0xffff0000, v73
	v_lshlrev_b32_e32 v171, 16, v74
	v_and_b32_e32 v172, 0xffff0000, v74
	v_lshlrev_b32_e32 v173, 16, v75
	v_mul_f32_e32 v174, v240, v168
	v_fmac_f32_e32 v174, v241, v169
	v_fmac_f32_e32 v174, v242, v170
	v_add_f32_e32 v174, v243, v174
	v_mul_f32_e32 v175, v240, v169
	v_fmac_f32_e32 v175, v241, v170
	v_fmac_f32_e32 v175, v242, v171
	v_add_f32_e32 v175, v243, v175
	v_mul_f32_e32 v176, v240, v170
	v_fmac_f32_e32 v176, v241, v171
	v_fmac_f32_e32 v176, v242, v172
	v_add_f32_e32 v176, v243, v176
	v_mul_f32_e32 v177, v240, v171
	v_fmac_f32_e32 v177, v241, v172
	v_fmac_f32_e32 v177, v242, v173
	v_add_f32_e32 v177, v243, v177
	v_mul_f32_e32 v174, v239, v174
	v_mul_f32_e32 v175, v239, v175
	v_mul_f32_e32 v176, v239, v176
	v_mul_f32_e32 v177, v239, v177
	v_fmac_f32_e32 v174, v238, v0
	v_fmac_f32_e32 v175, v238, v1
	v_fmac_f32_e32 v176, v238, v2
	v_fmac_f32_e32 v177, v238, v3
	v_and_b32_e32 v168, 0xffff0000, v76
	v_lshlrev_b32_e32 v169, 16, v77
	v_and_b32_e32 v170, 0xffff0000, v77
	v_lshlrev_b32_e32 v171, 16, v78
	v_and_b32_e32 v172, 0xffff0000, v78
	v_lshlrev_b32_e32 v173, 16, v79
	v_mul_f32_e32 v178, v244, v168
	v_fmac_f32_e32 v178, v245, v169
	v_fmac_f32_e32 v178, v246, v170
	v_add_f32_e32 v178, v247, v178
	v_mul_f32_e32 v179, v244, v169
	v_fmac_f32_e32 v179, v245, v170
	v_fmac_f32_e32 v179, v246, v171
	v_add_f32_e32 v179, v247, v179
	v_mul_f32_e32 v180, v244, v170
	v_fmac_f32_e32 v180, v245, v171
	v_fmac_f32_e32 v180, v246, v172
	v_add_f32_e32 v180, v247, v180
	v_mul_f32_e32 v181, v244, v171
	v_fmac_f32_e32 v181, v245, v172
	v_fmac_f32_e32 v181, v246, v173
	v_add_f32_e32 v181, v247, v181
	v_mul_f32_e32 v174, v174, v178
	v_mul_f32_e32 v175, v175, v179
	v_mul_f32_e32 v176, v176, v180
	v_mul_f32_e32 v177, v177, v181
	v_cvt_pk_bf16_f32 v182, v174, v175
	v_cvt_pk_bf16_f32 v183, v176, v177
	ds_write_b64 v235, v[182:183] offset:192
	v_and_b32_e32 v168, 0xffff0000, v80
	v_lshlrev_b32_e32 v169, 16, v81
	v_and_b32_e32 v170, 0xffff0000, v81
	v_lshlrev_b32_e32 v171, 16, v82
	v_and_b32_e32 v172, 0xffff0000, v82
	v_lshlrev_b32_e32 v173, 16, v83
	v_mul_f32_e32 v174, v240, v168
	v_fmac_f32_e32 v174, v241, v169
	v_fmac_f32_e32 v174, v242, v170
	v_add_f32_e32 v174, v243, v174
	v_mul_f32_e32 v175, v240, v169
	v_fmac_f32_e32 v175, v241, v170
	v_fmac_f32_e32 v175, v242, v171
	v_add_f32_e32 v175, v243, v175
	v_mul_f32_e32 v176, v240, v170
	v_fmac_f32_e32 v176, v241, v171
	v_fmac_f32_e32 v176, v242, v172
	v_add_f32_e32 v176, v243, v176
	v_mul_f32_e32 v177, v240, v171
	v_fmac_f32_e32 v177, v241, v172
	v_fmac_f32_e32 v177, v242, v173
	v_add_f32_e32 v177, v243, v177
	v_mul_f32_e32 v174, v239, v174
	v_mul_f32_e32 v175, v239, v175
	v_mul_f32_e32 v176, v239, v176
	v_mul_f32_e32 v177, v239, v177
	v_fmac_f32_e32 v174, v238, v4
; DI float bf2f(unsigned v) { return __uint_as_float(v << 16); }
; DI float bflo(unsigned v) { return __uint_as_float(v << 16); }
; DI float bfhi(unsigned v) { return __uint_as_float(v & 0xffff0000u); }
; DI void sconv4(const u16* row, int t4, float w0, float w1, float w2, float bias, float (&o)[4]) {
;   const uint2 v = *(const uint2*)(row + t4);
;   const float x0 = bflo(v.x), x1 = bfhi(v.x), x2 = bflo(v.y), x3 = bfhi(v.y);
;   const float xm = (t4 > 0) ? bf2f(row[t4 - 1]) : 0.f;
;   const float xp = (t4 + 4 < SEQ) ? bf2f(row[t4 + 4]) : 0.f;
;   o[0] = w0 * xm + w1 * x0 + w2 * x1 + bias;
;   o[1] = w0 * x0 + w1 * x1 + w2 * x2 + bias;
;   o[2] = w0 * x1 + w1 * x2 + w2 * x3 + bias;
;   o[3] = w0 * x2 + w1 * x3 + w2 * xp + bias;
; }
; DI void hyena_item(const P& p, int l, int c, char* smem) {
;     ...
; #pragma unroll
;     for (int I = 0; I < 4; ++I)
; #pragma unroll
;       for (int rq = 0; rq < 4; ++rq) {
;         const int bq = 32 * I + 8 * rq + 4 * g;
;         const int t4 = 128 * a + bq;
;         float pv[4], px[4];
;         sconv4(rowv, t4, v0, v1, v2, vb, pv);
;         sconv4(rowx, t4, x0, x1, x2, xb, px);
;         float zz[4];
; #pragma unroll
;         for (int j = 0; j < 4; ++j) zz[j] = px[j] * (acc[I][4 * rq + j] * invn0 + pv[j] * d0);
;         uint2 ov; ov.x = pack2(zz[0], zz[1]); ov.y = pack2(zz[2], zz[3]);
;         *(uint2*)(U + (bt * 64 + a) * 136 + bq) = ov;
;       }
	v_fmac_f32_e32 v175, v238, v5
	v_fmac_f32_e32 v176, v238, v6
	v_fmac_f32_e32 v177, v238, v7
	v_and_b32_e32 v168, 0xffff0000, v84
	v_lshlrev_b32_e32 v169, 16, v85
	v_and_b32_e32 v170, 0xffff0000, v85
	v_lshlrev_b32_e32 v171, 16, v86
	v_and_b32_e32 v172, 0xffff0000, v86
	v_lshlrev_b32_e32 v173, 16, v87
	v_mul_f32_e32 v178, v244, v168
	v_fmac_f32_e32 v178, v245, v169
	v_fmac_f32_e32 v178, v246, v170
	v_add_f32_e32 v178, v247, v178
	v_mul_f32_e32 v179, v244, v169
	v_fmac_f32_e32 v179, v245, v170
	v_fmac_f32_e32 v179, v246, v171
	v_add_f32_e32 v179, v247, v179
	v_mul_f32_e32 v180, v244, v170
	v_fmac_f32_e32 v180, v245, v171
	v_fmac_f32_e32 v180, v246, v172
	v_add_f32_e32 v180, v247, v180
	v_mul_f32_e32 v181, v244, v171
	v_fmac_f32_e32 v181, v245, v172
	v_fmac_f32_e32 v181, v246, v173
	v_add_f32_e32 v181, v247, v181
	v_mul_f32_e32 v174, v174, v178
	v_mul_f32_e32 v175, v175, v179
	v_mul_f32_e32 v176, v176, v180
	v_mul_f32_e32 v177, v177, v181
	v_cvt_pk_bf16_f32 v182, v174, v175
	v_cvt_pk_bf16_f32 v183, v176, v177
	ds_write_b64 v235, v[182:183] offset:208
	v_and_b32_e32 v168, 0xffff0000, v88
	v_lshlrev_b32_e32 v169, 16, v89
	v_and_b32_e32 v170, 0xffff0000, v89
	v_lshlrev_b32_e32 v171, 16, v90
	v_and_b32_e32 v172, 0xffff0000, v90
	v_lshlrev_b32_e32 v173, 16, v91
	v_mul_f32_e32 v174, v240, v168
	v_fmac_f32_e32 v174, v241, v169
	v_fmac_f32_e32 v174, v242, v170
	v_add_f32_e32 v174, v243, v174
	v_mul_f32_e32 v175, v240, v169
	v_fmac_f32_e32 v175, v241, v170
	v_fmac_f32_e32 v175, v242, v171
	v_add_f32_e32 v175, v243, v175
	v_mul_f32_e32 v176, v240, v170
	v_fmac_f32_e32 v176, v241, v171
	v_fmac_f32_e32 v176, v242, v172
	v_add_f32_e32 v176, v243, v176
	v_mul_f32_e32 v177, v240, v171
	v_fmac_f32_e32 v177, v241, v172
	v_fmac_f32_e32 v177, v242, v173
	v_add_f32_e32 v177, v243, v177
	v_mul_f32_e32 v174, v239, v174
	v_mul_f32_e32 v175, v239, v175
	v_mul_f32_e32 v176, v239, v176
	v_mul_f32_e32 v177, v239, v177
	v_fmac_f32_e32 v174, v238, v8
	v_fmac_f32_e32 v175, v238, v9
	v_fmac_f32_e32 v176, v238, v10
	v_fmac_f32_e32 v177, v238, v11
	v_and_b32_e32 v168, 0xffff0000, v92
	v_lshlrev_b32_e32 v169, 16, v93
	v_and_b32_e32 v170, 0xffff0000, v93
	v_lshlrev_b32_e32 v171, 16, v94
	v_and_b32_e32 v172, 0xffff0000, v94
	v_lshlrev_b32_e32 v173, 16, v95
	v_mul_f32_e32 v178, v244, v168
	v_fmac_f32_e32 v178, v245, v169
	v_fmac_f32_e32 v178, v246, v170
	v_add_f32_e32 v178, v247, v178
	v_mul_f32_e32 v179, v244, v169
	v_fmac_f32_e32 v179, v245, v170
	v_fmac_f32_e32 v179, v246, v171
	v_add_f32_e32 v179, v247, v179
	v_mul_f32_e32 v180, v244, v170
	v_fmac_f32_e32 v180, v245, v171
	v_fmac_f32_e32 v180, v246, v172
	v_add_f32_e32 v180, v247, v180
	v_mul_f32_e32 v181, v244, v171
	v_fmac_f32_e32 v181, v245, v172
	v_fmac_f32_e32 v181, v246, v173
	v_add_f32_e32 v181, v247, v181
	v_mul_f32_e32 v174, v174, v178
	v_mul_f32_e32 v175, v175, v179
	v_mul_f32_e32 v176, v176, v180
	v_mul_f32_e32 v177, v177, v181
	v_cvt_pk_bf16_f32 v182, v174, v175
	v_cvt_pk_bf16_f32 v183, v176, v177
	ds_write_b64 v235, v[182:183] offset:224
	v_cmp_ne_u32_e32 vcc, 0x1f84, v233
	s_nop 1
	v_and_b32_e32 v168, 0xffff0000, v96
	v_lshlrev_b32_e32 v169, 16, v97
	v_and_b32_e32 v170, 0xffff0000, v97
	v_lshlrev_b32_e32 v171, 16, v98
	v_and_b32_e32 v172, 0xffff0000, v98
	v_lshlrev_b32_e32 v173, 16, v99
	v_cndmask_b32_e32 v173, 0, v173, vcc
	v_mul_f32_e32 v174, v240, v168
	v_fmac_f32_e32 v174, v241, v169
	v_fmac_f32_e32 v174, v242, v170
	v_add_f32_e32 v174, v243, v174
	v_mul_f32_e32 v175, v240, v169
	v_fmac_f32_e32 v175, v241, v170
	v_fmac_f32_e32 v175, v242, v171
	v_add_f32_e32 v175, v243, v175
	v_mul_f32_e32 v176, v240, v170
	v_fmac_f32_e32 v176, v241, v171
	v_fmac_f32_e32 v176, v242, v172
	v_add_f32_e32 v176, v243, v176
	v_mul_f32_e32 v177, v240, v171
	v_fmac_f32_e32 v177, v241, v172
	v_fmac_f32_e32 v177, v242, v173
	v_add_f32_e32 v177, v243, v177
	v_mul_f32_e32 v174, v239, v174
	v_mul_f32_e32 v175, v239, v175
	v_mul_f32_e32 v176, v239, v176
	v_mul_f32_e32 v177, v239, v177
	v_fmac_f32_e32 v174, v238, v12
	v_fmac_f32_e32 v175, v238, v13
	v_fmac_f32_e32 v176, v238, v14
	v_fmac_f32_e32 v177, v238, v15
	v_and_b32_e32 v168, 0xffff0000, v100
	v_lshlrev_b32_e32 v169, 16, v101
	v_and_b32_e32 v170, 0xffff0000, v101
	v_lshlrev_b32_e32 v171, 16, v102
	v_and_b32_e32 v172, 0xffff0000, v102
	v_lshlrev_b32_e32 v173, 16, v103
	v_cndmask_b32_e32 v173, 0, v173, vcc
	v_mul_f32_e32 v178, v244, v168
	v_fmac_f32_e32 v178, v245, v169
	v_fmac_f32_e32 v178, v246, v170
	v_add_f32_e32 v178, v247, v178
	v_mul_f32_e32 v179, v244, v169
	v_fmac_f32_e32 v179, v245, v170
	v_fmac_f32_e32 v179, v246, v171
	v_add_f32_e32 v179, v247, v179
	v_mul_f32_e32 v180, v244, v170
	v_fmac_f32_e32 v180, v245, v171
	v_fmac_f32_e32 v180, v246, v172
	v_add_f32_e32 v180, v247, v180
	v_mul_f32_e32 v181, v244, v171
	v_fmac_f32_e32 v181, v245, v172
	v_fmac_f32_e32 v181, v246, v173
	v_add_f32_e32 v181, v247, v181
	v_mul_f32_e32 v174, v174, v178
	v_mul_f32_e32 v175, v175, v179
	v_mul_f32_e32 v176, v176, v180
	v_mul_f32_e32 v177, v177, v181
	v_cvt_pk_bf16_f32 v182, v174, v175
	v_cvt_pk_bf16_f32 v183, v176, v177
	ds_write_b64 v235, v[182:183] offset:240
